# P4 stage wave 0: last-token log-decay broadcast with v_readlane (scalar) instead of ds_bpermute + wait
# baseline (speedup 1.0000x reference)
.Lp4n_cwkeep_A:
	v_lshlrev_b32_e32 v102, 16, v128
	v_and_b32_e32 v103, 0xffff0000, v128
	v_pk_mul_f32 v[102:103], v[94:95], v[102:103]
	v_lshlrev_b32_e32 v104, 16, v129
	v_and_b32_e32 v105, 0xffff0000, v129
	v_pk_mul_f32 v[104:105], v[96:97], v[104:105]
	v_lshlrev_b32_e32 v106, 16, v130
	v_and_b32_e32 v107, 0xffff0000, v130
	v_pk_fma_f32 v[102:103], v[90:91], v[106:107], v[102:103]
	v_lshlrev_b32_e32 v108, 16, v131
	v_and_b32_e32 v109, 0xffff0000, v131
	v_pk_fma_f32 v[104:105], v[92:93], v[108:109], v[104:105]
	v_lshlrev_b32_e32 v106, 16, v132
	v_and_b32_e32 v107, 0xffff0000, v132
	v_pk_fma_f32 v[102:103], v[86:87], v[106:107], v[102:103]
	v_lshlrev_b32_e32 v108, 16, v133
	v_and_b32_e32 v109, 0xffff0000, v133
	v_pk_fma_f32 v[104:105], v[88:89], v[108:109], v[104:105]
	v_lshlrev_b32_e32 v106, 16, v136
	v_and_b32_e32 v107, 0xffff0000, v136
	v_pk_fma_f32 v[102:103], v[82:83], v[106:107], v[102:103]
	v_lshlrev_b32_e32 v108, 16, v137
	v_and_b32_e32 v109, 0xffff0000, v137
	v_pk_fma_f32 v[104:105], v[84:85], v[108:109], v[104:105]
	v_pk_mul_f32 v[106:107], v[102:103], s[100:101] op_sel_hi:[1,0]
	v_pk_mul_f32 v[108:109], v[104:105], s[100:101] op_sel_hi:[1,0]
	v_exp_f32_e32 v106, v106
	v_exp_f32_e32 v107, v107
	v_exp_f32_e32 v108, v108
	v_exp_f32_e32 v109, v109
	v_pk_add_f32 v[106:107], v[106:107], 1.0 op_sel_hi:[1,0]
	v_pk_add_f32 v[108:109], v[108:109], 1.0 op_sel_hi:[1,0]
	v_rcp_f32_e32 v106, v106
	v_rcp_f32_e32 v107, v107
	v_rcp_f32_e32 v108, v108
	v_rcp_f32_e32 v109, v109
	v_pk_mul_f32 v[102:103], v[102:103], v[106:107]
	v_pk_mul_f32 v[104:105], v[104:105], v[108:109]
	s_waitcnt vmcnt(7)
	v_mul_f32_e32 v102, v175, v102
	v_mul_f32_e32 v103, v175, v103
	v_mul_f32_e32 v104, v175, v104
	v_mul_f32_e32 v105, v175, v105
	v_cvt_pk_bf16_f32 v102, v102, s0
	v_cvt_pk_bf16_f32 v103, v103, s0
	v_cvt_pk_bf16_f32 v104, v104, s0
	v_cvt_pk_bf16_f32 v105, v105, s0
	ds_write_b16 v197, v102 offset:26624
	ds_write_b16 v197, v103 offset:26768
	ds_write_b16 v197, v104 offset:26912
	ds_write_b16 v197, v105 offset:27056
	s_and_saveexec_b64 s[8:9], s[4:5]
	s_cbranch_execz .Lp4n_w0done_A
	s_mov_b32 s14, 0x1d900
	s_and_b64 s[20:21], vcc, exec
	s_cselect_b32 s20, 63, 0
	v_mul_f32_e32 v103, 0x3fb8aa3b, v176
	v_exp_f32_e32 v103, v103
	v_lshl_add_u32 v105, v0, 2, s14
	s_nop 0
	v_readlane_b32 s21, v176, s20
	s_nop 1
	v_sub_f32_e32 v104, s21, v176
	v_mov_b32_e32 v102, s21
	v_mul_f32_e32 v104, 0x3fb8aa3b, v104
	v_exp_f32_e32 v104, v104
	v_mul_f32_e32 v106, v177, v103
	ds_write2st64_b32 v105, v103, v106 offset1:1
	ds_write_b32 v105, v104 offset:512
	s_and_b64 exec, exec, s[6:7]
	s_cbranch_execz .Lp4n_w0done_A
	v_mul_f32_e32 v102, 0x3fb8aa3b, v102
	v_exp_f32_e32 v102, v102
	v_mov_b32_e32 v103, s14
	ds_write_b32 v103, v102 offset:768

.Lp4n_cwkeep_B:
	v_lshlrev_b32_e32 v2, 16, v134
	v_and_b32_e32 v3, 0xffff0000, v134
	v_pk_mul_f32 v[2:3], v[94:95], v[2:3]
	v_lshlrev_b32_e32 v4, 16, v135
	v_and_b32_e32 v5, 0xffff0000, v135
	v_pk_mul_f32 v[4:5], v[96:97], v[4:5]
	v_lshlrev_b32_e32 v6, 16, v138
	v_and_b32_e32 v7, 0xffff0000, v138
	v_pk_fma_f32 v[2:3], v[90:91], v[6:7], v[2:3]
	v_lshlrev_b32_e32 v8, 16, v139
	v_and_b32_e32 v9, 0xffff0000, v139
	v_pk_fma_f32 v[4:5], v[92:93], v[8:9], v[4:5]
	v_lshlrev_b32_e32 v6, 16, v140
	v_and_b32_e32 v7, 0xffff0000, v140
	v_pk_fma_f32 v[2:3], v[86:87], v[6:7], v[2:3]
	v_lshlrev_b32_e32 v8, 16, v141
	v_and_b32_e32 v9, 0xffff0000, v141
	v_pk_fma_f32 v[4:5], v[88:89], v[8:9], v[4:5]
	v_lshlrev_b32_e32 v6, 16, v142
	v_and_b32_e32 v7, 0xffff0000, v142
	v_pk_fma_f32 v[2:3], v[82:83], v[6:7], v[2:3]
	v_lshlrev_b32_e32 v8, 16, v143
	v_and_b32_e32 v9, 0xffff0000, v143
	v_pk_fma_f32 v[4:5], v[84:85], v[8:9], v[4:5]
	v_pk_mul_f32 v[6:7], v[2:3], s[100:101] op_sel_hi:[1,0]
	v_pk_mul_f32 v[8:9], v[4:5], s[100:101] op_sel_hi:[1,0]
	v_exp_f32_e32 v6, v6
	v_exp_f32_e32 v7, v7
	v_exp_f32_e32 v8, v8
	v_exp_f32_e32 v9, v9
	v_pk_add_f32 v[6:7], v[6:7], 1.0 op_sel_hi:[1,0]
	v_pk_add_f32 v[8:9], v[8:9], 1.0 op_sel_hi:[1,0]
	v_rcp_f32_e32 v6, v6
	v_rcp_f32_e32 v7, v7
	v_rcp_f32_e32 v8, v8
	v_rcp_f32_e32 v9, v9
	v_pk_mul_f32 v[2:3], v[2:3], v[6:7]
	v_pk_mul_f32 v[4:5], v[4:5], v[8:9]
	s_waitcnt vmcnt(7)
	v_mul_f32_e32 v2, v181, v2
	v_mul_f32_e32 v3, v181, v3
	v_mul_f32_e32 v4, v181, v4
	v_mul_f32_e32 v5, v181, v5
	v_cvt_pk_bf16_f32 v2, v2, s0
	v_cvt_pk_bf16_f32 v3, v3, s0
	v_cvt_pk_bf16_f32 v4, v4, s0
	v_cvt_pk_bf16_f32 v5, v5, s0
	ds_write_b16 v197, v2 offset:26624
	ds_write_b16 v197, v3 offset:26768
	ds_write_b16 v197, v4 offset:26912
	ds_write_b16 v197, v5 offset:27056
	s_and_saveexec_b64 s[8:9], s[4:5]
	s_cbranch_execz .Lp4n_w0done_B
	s_mov_b32 s14, 0x1d400
	s_and_b64 s[20:21], vcc, exec
	s_cselect_b32 s20, 63, 0
	v_mul_f32_e32 v3, 0x3fb8aa3b, v184
	v_exp_f32_e32 v3, v3
	v_lshl_add_u32 v5, v0, 2, s14
	s_nop 0
	v_readlane_b32 s21, v184, s20
	s_nop 1
	v_sub_f32_e32 v4, s21, v184
	v_mov_b32_e32 v2, s21
	v_mul_f32_e32 v4, 0x3fb8aa3b, v4
	v_exp_f32_e32 v4, v4
	v_mul_f32_e32 v6, v185, v3
	ds_write2st64_b32 v5, v3, v6 offset1:1
	ds_write_b32 v5, v4 offset:512
	s_and_b64 exec, exec, s[6:7]
	s_cbranch_execz .Lp4n_w0done_B
	v_mul_f32_e32 v2, 0x3fb8aa3b, v2
	v_exp_f32_e32 v2, v2
	v_mov_b32_e32 v3, s14
	ds_write_b32 v3, v2 offset:768
